# speedup vs baseline: 1.0196x; 1.0196x over previous
.LBB0_150:
	s_mul_i32 s3, s2, 0xd800
	v_add_u32_e32 v138, s3, v132
	ds_read_b128 v[170:173], v138
	ds_read_b128 v[174:177], v138 offset:4608
	ds_read_b128 v[178:181], v138 offset:9216
	ds_read_b128 v[182:185], v138 offset:13824
	ds_read_b128 v[186:189], v138 offset:64
	ds_read_b128 v[190:193], v138 offset:4672
	ds_read_b128 v[194:197], v138 offset:9280
	ds_read_b128 v[198:201], v138 offset:13888
	ds_read_b128 v[202:205], v138 offset:128
	ds_read_b128 v[206:209], v138 offset:4736
	ds_read_b128 v[210:213], v138 offset:9344
	ds_read_b128 v[214:217], v138 offset:13952
	v_add_u32_e32 v166, s53, v66
	v_subrev_u32_e32 v165, 63, v166
	s_mov_b64 s[4:5], -1
	s_and_b64 vcc, exec, s[0:1]
	s_waitcnt lgkmcnt(8)
	v_mfma_f32_16x16x32_bf16 v[110:113], v[170:173], v[0:3], 0
	v_mfma_f32_16x16x32_bf16 v[114:117], v[174:177], v[0:3], 0
	v_mfma_f32_16x16x32_bf16 v[118:121], v[178:181], v[0:3], 0
	v_mfma_f32_16x16x32_bf16 v[122:125], v[182:185], v[0:3], 0
	ds_read_b128 v[218:221], v138 offset:192
	ds_read_b128 v[222:225], v138 offset:4800
	ds_read_b128 v[226:229], v138 offset:9408
	ds_read_b128 v[230:233], v138 offset:14016
	s_waitcnt lgkmcnt(8)
	v_mfma_f32_16x16x32_bf16 v[110:113], v[186:189], v[4:7], v[110:113]
	v_mfma_f32_16x16x32_bf16 v[114:117], v[190:193], v[4:7], v[114:117]
	v_mfma_f32_16x16x32_bf16 v[118:121], v[194:197], v[4:7], v[118:121]
	v_mfma_f32_16x16x32_bf16 v[122:125], v[198:201], v[4:7], v[122:125]
	s_waitcnt lgkmcnt(4)
	v_mfma_f32_16x16x32_bf16 v[110:113], v[202:205], v[8:11], v[110:113]
	v_mfma_f32_16x16x32_bf16 v[114:117], v[206:209], v[8:11], v[114:117]
	v_mfma_f32_16x16x32_bf16 v[118:121], v[210:213], v[8:11], v[118:121]
	v_mfma_f32_16x16x32_bf16 v[122:125], v[214:217], v[8:11], v[122:125]
	s_waitcnt lgkmcnt(0)
	v_mfma_f32_16x16x32_bf16 v[110:113], v[218:221], v[12:15], v[110:113]
	v_mfma_f32_16x16x32_bf16 v[114:117], v[222:225], v[12:15], v[114:117]
	v_mfma_f32_16x16x32_bf16 v[140:143], v[226:229], v[12:15], v[118:121]
	v_mfma_f32_16x16x32_bf16 v[144:147], v[230:233], v[12:15], v[122:125]
	ds_read_b128 v[170:173], v138 offset:18432
	ds_read_b128 v[174:177], v138 offset:18496
	ds_read_b128 v[178:181], v138 offset:23040
	ds_read_b128 v[182:185], v138 offset:23104
	ds_read_b128 v[186:189], v138 offset:27648
	ds_read_b128 v[190:193], v138 offset:27712
	ds_read_b128 v[194:197], v138 offset:32256
	ds_read_b128 v[198:201], v138 offset:32320
	ds_read_b128 v[202:205], v138 offset:36864
	ds_read_b128 v[206:209], v138 offset:36928
	ds_read_b128 v[210:213], v138 offset:41472
	ds_read_b128 v[214:217], v138 offset:41536
	v_fma_f32 v124, v110, s74, v72
	v_fma_f32 v125, v111, s74, v73
	v_pk_fma_f32 v[122:123], v[112:113], s[74:75], v[74:75] op_sel_hi:[1,0,1]
	v_pk_fma_f32 v[118:119], v[114:115], s[74:75], v[76:77] op_sel_hi:[1,0,1]
	v_pk_fma_f32 v[120:121], v[116:117], s[74:75], v[78:79] op_sel_hi:[1,0,1]
	v_pk_fma_f32 v[116:117], v[140:141], s[74:75], v[80:81] op_sel_hi:[1,0,1]
	v_pk_fma_f32 v[112:113], v[142:143], s[74:75], v[82:83] op_sel_hi:[1,0,1]
	v_pk_fma_f32 v[114:115], v[144:145], s[74:75], v[84:85] op_sel_hi:[1,0,1]
	v_pk_fma_f32 v[110:111], v[146:147], s[74:75], v[86:87] op_sel_hi:[1,0,1]
	s_cbranch_vccz .LBB0_154
	v_cmp_gt_i32_e32 vcc, s53, v130
	s_and_b64 s[34:35], s[60:61], vcc
	v_mov_b32_e32 v140, v111
	v_mov_b32_e32 v141, v110
	v_mov_b32_e32 v142, v115
	v_mov_b32_e32 v143, v114
	v_mov_b32_e32 v144, v113
	v_mov_b32_e32 v145, v112
	v_mov_b32_e32 v146, v117
	v_mov_b32_e32 v147, v116
	v_mov_b32_e32 v157, v121
	v_mov_b32_e32 v158, v120
	v_mov_b32_e32 v159, v119
	v_mov_b32_e32 v160, v118
	v_mov_b32_e32 v161, v123
	v_mov_b32_e32 v162, v122
	v_mov_b32_e32 v163, v125
	v_mov_b32_e32 v164, v124
	s_and_saveexec_b64 s[4:5], s[34:35]
	s_cbranch_execz .LBB0_153
	v_cmp_ge_i32_e32 vcc, v131, v165
	v_subrev_u32_e32 v140, 61, v166
	s_nop 0
	v_cndmask_b32_e32 v164, v152, v124, vcc
	v_cmp_gt_i32_e32 vcc, v131, v165
	s_nop 1
	v_cndmask_b32_e32 v163, v152, v125, vcc
	v_cmp_ge_i32_e32 vcc, v131, v140
	v_subrev_u32_e32 v140, 60, v166
	s_nop 0
	v_cndmask_b32_e32 v162, v152, v122, vcc
	v_cmp_ge_i32_e32 vcc, v131, v140
	v_subrev_u32_e32 v140, 59, v166
	s_nop 0
	v_cndmask_b32_e32 v161, v152, v123, vcc
	v_cmp_ge_i32_e32 vcc, v131, v140
	v_subrev_u32_e32 v140, 58, v166
	s_nop 0
	v_cndmask_b32_e32 v160, v152, v118, vcc
	v_cmp_ge_i32_e32 vcc, v131, v140
	v_subrev_u32_e32 v140, 57, v166
	s_nop 0
	v_cndmask_b32_e32 v159, v152, v119, vcc
	v_cmp_ge_i32_e32 vcc, v131, v140
	v_subrev_u32_e32 v140, 56, v166
	s_nop 0
	v_cndmask_b32_e32 v158, v152, v120, vcc
	v_cmp_ge_i32_e32 vcc, v131, v140
	v_subrev_u32_e32 v140, 31, v166
	s_nop 0
	v_cndmask_b32_e32 v157, v152, v121, vcc
	v_cmp_ge_i32_e32 vcc, v131, v140
	v_subrev_u32_e32 v140, 30, v166
	s_nop 0
	v_cndmask_b32_e32 v147, v152, v116, vcc
	v_cmp_ge_i32_e32 vcc, v131, v140
	v_subrev_u32_e32 v140, 29, v166
	s_nop 0
	v_cndmask_b32_e32 v146, v152, v117, vcc
	v_cmp_ge_i32_e32 vcc, v131, v140
	v_subrev_u32_e32 v140, 28, v166
	s_nop 0
	v_cndmask_b32_e32 v145, v152, v112, vcc
	v_cmp_ge_i32_e32 vcc, v131, v140
	v_subrev_u32_e32 v140, 27, v166
	s_nop 0
	v_cndmask_b32_e32 v144, v152, v113, vcc
	v_cmp_ge_i32_e32 vcc, v131, v140
	v_subrev_u32_e32 v140, 26, v166
	s_nop 0
	v_cndmask_b32_e32 v143, v152, v114, vcc
	v_cmp_ge_i32_e32 vcc, v131, v140
	v_subrev_u32_e32 v140, 25, v166
	s_nop 0
	v_cndmask_b32_e32 v142, v152, v115, vcc
	v_cmp_ge_i32_e32 vcc, v131, v140
	v_subrev_u32_e32 v140, 24, v166
	s_nop 0
	v_cndmask_b32_e32 v141, v152, v110, vcc
	v_cmp_ge_i32_e32 vcc, v131, v140
	s_nop 1
	v_cndmask_b32_e32 v140, v152, v111, vcc

.LBB0_156:
	s_ashr_i32 s3, s45, 8
	s_lshl_b32 s3, 1, s3
	v_and_b32_e32 v110, s3, v126
	v_cmp_eq_u32_e32 vcc, 0, v110
	v_max_f32_e32 v110, v163, v163
	v_max_f32_e32 v111, v164, v164
	v_max_f32_e32 v110, v111, v110
	v_max3_f32 v110, v110, v162, v161
	v_max3_f32 v110, v110, v160, v159
	v_max3_f32 v110, v110, v158, v157
	v_max3_f32 v110, v110, v147, v146
	v_max3_f32 v110, v110, v145, v144
	v_max3_f32 v110, v110, v143, v142
	v_max3_f32 v110, v110, v141, v140
	s_and_b64 s[4:5], s[60:61], vcc
	v_cndmask_b32_e64 v110, v110, v152, s[4:5]
	ds_bpermute_b32 v111, v97, v110
	v_add_u32_e32 v112, s53, v101
	v_subrev_u32_e32 v112, 63, v112
	v_cvt_f32_i32_e32 v112, v112
	s_waitcnt lgkmcnt(0)
	v_max_f32_e32 v111, v111, v111
	v_max_f32_e32 v110, v110, v111
	ds_bpermute_b32 v111, v99, v110
	s_waitcnt lgkmcnt(0)
	ds_read_b128 v[218:221], v138 offset:46080
	ds_read_b128 v[222:225], v138 offset:46144
	ds_read_b128 v[226:229], v138 offset:50688
	ds_read_b128 v[230:233], v138 offset:50752
	v_max_f32_e32 v111, v111, v111
	v_max_f32_e32 v110, v110, v111
	v_fmac_f32_e32 v110, v68, v112
	v_max_f32_e32 v111, v139, v139
	v_max_f32_e32 v111, v111, v110
	v_sub_f32_e32 v110, v139, v111
	v_exp_f32_e32 v110, v110
	s_nop 0
	v_cmp_neq_f32_e32 vcc, 1.0, v110
	s_cbranch_vccz .LBB0_158
	v_pk_mul_f32 v[58:59], v[58:59], v[110:111] op_sel_hi:[1,0]
	v_pk_mul_f32 v[56:57], v[56:57], v[110:111] op_sel_hi:[1,0]
	v_pk_mul_f32 v[62:63], v[62:63], v[110:111] op_sel_hi:[1,0]
	v_pk_mul_f32 v[60:61], v[60:61], v[110:111] op_sel_hi:[1,0]
	v_pk_mul_f32 v[54:55], v[54:55], v[110:111] op_sel_hi:[1,0]
	v_pk_mul_f32 v[52:53], v[52:53], v[110:111] op_sel_hi:[1,0]
	v_pk_mul_f32 v[50:51], v[50:51], v[110:111] op_sel_hi:[1,0]
	v_pk_mul_f32 v[48:49], v[48:49], v[110:111] op_sel_hi:[1,0]
	v_pk_mul_f32 v[46:47], v[46:47], v[110:111] op_sel_hi:[1,0]
	v_pk_mul_f32 v[44:45], v[44:45], v[110:111] op_sel_hi:[1,0]
	v_pk_mul_f32 v[42:43], v[42:43], v[110:111] op_sel_hi:[1,0]
	v_pk_mul_f32 v[40:41], v[40:41], v[110:111] op_sel_hi:[1,0]
	v_pk_mul_f32 v[38:39], v[38:39], v[110:111] op_sel_hi:[1,0]
	v_pk_mul_f32 v[36:37], v[36:37], v[110:111] op_sel_hi:[1,0]
	v_pk_mul_f32 v[34:35], v[34:35], v[110:111] op_sel_hi:[1,0]
	v_pk_mul_f32 v[32:33], v[32:33], v[110:111] op_sel_hi:[1,0]
.LBB0_158:
	v_mul_f32_e32 v112, v68, v112
	v_sub_f32_e32 v112, v111, v112
	v_cndmask_b32_e64 v112, v112, v153, s[4:5]
	v_sub_f32_e32 v113, v164, v112
	v_exp_f32_e32 v113, v113
	v_sub_f32_e32 v115, v163, v112
	v_exp_f32_e32 v115, v115
	v_sub_f32_e32 v116, v162, v112
	v_exp_f32_e32 v117, v116
	v_sub_f32_e32 v116, v161, v112
	v_exp_f32_e32 v118, v116
	v_sub_f32_e32 v116, v160, v112
	v_add_f32_e32 v114, 0, v113
	v_exp_f32_e32 v119, v116
	v_sub_f32_e32 v116, v159, v112
	v_add_f32_e32 v114, v115, v114
	v_exp_f32_e32 v120, v116
	v_sub_f32_e32 v116, v158, v112
	v_add_f32_e32 v114, v117, v114
	v_exp_f32_e32 v121, v116
	v_sub_f32_e32 v116, v157, v112
	v_add_f32_e32 v114, v118, v114
	v_exp_f32_e32 v122, v116
	v_sub_f32_e32 v116, v147, v112
	v_add_f32_e32 v114, v119, v114
	v_exp_f32_e32 v116, v116
	v_sub_f32_e32 v123, v146, v112
	v_add_f32_e32 v114, v120, v114
	v_exp_f32_e32 v123, v123
	v_sub_f32_e32 v124, v145, v112
	v_add_f32_e32 v114, v121, v114
	v_exp_f32_e32 v124, v124
	v_sub_f32_e32 v125, v144, v112
	v_add_f32_e32 v114, v122, v114
	v_exp_f32_e32 v125, v125
	v_sub_f32_e32 v139, v143, v112
	v_add_f32_e32 v114, v116, v114
	v_exp_f32_e32 v139, v139
	v_sub_f32_e32 v142, v142, v112
	v_add_f32_e32 v114, v123, v114
	v_exp_f32_e32 v142, v142
	v_sub_f32_e32 v141, v141, v112
	v_add_f32_e32 v114, v124, v114
	v_exp_f32_e32 v141, v141
	v_sub_f32_e32 v112, v140, v112
	v_add_f32_e32 v114, v125, v114
	v_exp_f32_e32 v140, v112
	v_add_f32_e32 v114, v139, v114
	v_add_f32_e32 v114, v142, v114
	v_add_f32_e32 v114, v141, v114
	v_add_f32_e32 v144, v140, v114
	v_cvt_pk_bf16_f32 v112, v113, v115
	v_cvt_pk_bf16_f32 v116, v116, v123
	v_cvt_pk_bf16_f32 v113, v117, v118
	v_cvt_pk_bf16_f32 v114, v119, v120
	v_cvt_pk_bf16_f32 v118, v139, v142
	v_cvt_pk_bf16_f32 v115, v121, v122
	v_cvt_pk_bf16_f32 v119, v141, v140
	v_cvt_pk_bf16_f32 v117, v124, v125
	v_fmac_f32_e32 v144, v137, v110
	v_mov_b32_e32 v137, v144
	s_waitcnt lgkmcnt(0)
	v_mfma_f32_16x16x32_bf16 v[56:59], v[170:173], v[112:115], v[56:59]
	v_mfma_f32_16x16x32_bf16 v[60:63], v[178:181], v[112:115], v[60:63]
	v_mfma_f32_16x16x32_bf16 v[52:55], v[186:189], v[112:115], v[52:55]
	v_mfma_f32_16x16x32_bf16 v[48:51], v[194:197], v[112:115], v[48:51]
	v_mfma_f32_16x16x32_bf16 v[44:47], v[202:205], v[112:115], v[44:47]
	v_mfma_f32_16x16x32_bf16 v[40:43], v[210:213], v[112:115], v[40:43]
	v_mfma_f32_16x16x32_bf16 v[36:39], v[218:221], v[112:115], v[36:39]
	v_mfma_f32_16x16x32_bf16 v[32:35], v[226:229], v[112:115], v[32:35]
	v_mfma_f32_16x16x32_bf16 v[56:59], v[174:177], v[116:119], v[56:59]
	v_mfma_f32_16x16x32_bf16 v[60:63], v[182:185], v[116:119], v[60:63]
	v_mfma_f32_16x16x32_bf16 v[52:55], v[190:193], v[116:119], v[52:55]
	v_mfma_f32_16x16x32_bf16 v[48:51], v[198:201], v[116:119], v[48:51]
	v_mfma_f32_16x16x32_bf16 v[44:47], v[206:209], v[116:119], v[44:47]
	v_mfma_f32_16x16x32_bf16 v[40:43], v[214:217], v[116:119], v[40:43]
	v_mfma_f32_16x16x32_bf16 v[36:39], v[222:225], v[116:119], v[36:39]
	v_mfma_f32_16x16x32_bf16 v[32:35], v[230:233], v[116:119], v[32:35]
	v_mov_b32_e32 v139, v111
	s_or_b64 exec, exec, s[42:43]
	s_andn2_b64 vcc, exec, s[40:41]
	s_cbranch_vccnz .LBB0_137

.LBB0_187:
	ds_read_b128 v[176:179], v164
	ds_read_b128 v[180:183], v164 offset:1024
	ds_read_b128 v[184:187], v164 offset:2048
	ds_read_b128 v[188:191], v164 offset:3072
	s_add_u32 m0, s35, 0xc000
	ds_read_b128 v[192:195], v162
	ds_read_b128 v[196:199], v162 offset:1024
	ds_read_b128 v[200:203], v162 offset:2048
	ds_read_b128 v[204:207], v162 offset:3072
	ds_read_b128 v[208:211], v162 offset:4096
	ds_read_b128 v[212:215], v162 offset:5120
	ds_read_b128 v[216:219], v162 offset:6144
	ds_read_b128 v[220:223], v162 offset:7168
	global_load_lds_dwordx4 v128, s[76:77]
	s_add_u32 m0, s35, 0xe000
	s_nop 0
	global_load_lds_dwordx4 v130, s[76:77]
	s_add_u32 s76, s76, 0x80
	s_addc_u32 s77, s77, 0
	s_waitcnt lgkmcnt(8)
	s_barrier
	s_waitcnt lgkmcnt(0)
	s_setprio 1
	v_mfma_f32_16x16x32_bf16 v[124:127], v[176:179], v[192:195], v[124:127]
	v_mfma_f32_16x16x32_bf16 v[120:123], v[184:187], v[192:195], v[120:123]
	v_mfma_f32_16x16x32_bf16 v[116:119], v[176:179], v[200:203], v[116:119]
	v_mfma_f32_16x16x32_bf16 v[112:115], v[184:187], v[200:203], v[112:115]
	v_mfma_f32_16x16x32_bf16 v[108:111], v[176:179], v[208:211], v[108:111]
	v_mfma_f32_16x16x32_bf16 v[104:107], v[184:187], v[208:211], v[104:107]
	v_mfma_f32_16x16x32_bf16 v[100:103], v[176:179], v[216:219], v[100:103]
	v_mfma_f32_16x16x32_bf16 v[96:99], v[184:187], v[216:219], v[96:99]
	v_mfma_f32_16x16x32_bf16 v[124:127], v[180:183], v[196:199], v[124:127]
	v_mfma_f32_16x16x32_bf16 v[120:123], v[188:191], v[196:199], v[120:123]
	v_mfma_f32_16x16x32_bf16 v[116:119], v[180:183], v[204:207], v[116:119]
	v_mfma_f32_16x16x32_bf16 v[112:115], v[188:191], v[204:207], v[112:115]
	v_mfma_f32_16x16x32_bf16 v[108:111], v[180:183], v[212:215], v[108:111]
	v_mfma_f32_16x16x32_bf16 v[104:107], v[188:191], v[212:215], v[104:107]
	v_mfma_f32_16x16x32_bf16 v[100:103], v[180:183], v[220:223], v[100:103]
	v_mfma_f32_16x16x32_bf16 v[96:99], v[188:191], v[220:223], v[96:99]
	s_setprio 0
	s_barrier
	ds_read_b128 v[224:227], v164 offset:16384
	ds_read_b128 v[228:231], v164 offset:17408
	ds_read_b128 v[232:235], v164 offset:18432
	ds_read_b128 v[236:239], v164 offset:19456
	s_add_u32 m0, s35, 0x10000
	global_load_lds_dwordx4 v128, s[42:43]
	s_add_u32 m0, s35, 0x12000
	s_nop 0
	global_load_lds_dwordx4 v130, s[42:43]
	s_add_u32 s42, s42, 0x80
	s_addc_u32 s43, s43, 0
	s_add_i32 s34, s34, 2
	s_barrier
	s_waitcnt lgkmcnt(0)
	s_setprio 1
	v_mfma_f32_16x16x32_bf16 v[92:95], v[224:227], v[192:195], v[92:95]
	v_mfma_f32_16x16x32_bf16 v[88:91], v[232:235], v[192:195], v[88:91]
	v_mfma_f32_16x16x32_bf16 v[84:87], v[224:227], v[200:203], v[84:87]
	v_mfma_f32_16x16x32_bf16 v[80:83], v[232:235], v[200:203], v[80:83]
	v_mfma_f32_16x16x32_bf16 v[76:79], v[224:227], v[208:211], v[76:79]
	v_mfma_f32_16x16x32_bf16 v[72:75], v[232:235], v[208:211], v[72:75]
	v_mfma_f32_16x16x32_bf16 v[68:71], v[224:227], v[216:219], v[68:71]
	v_mfma_f32_16x16x32_bf16 v[64:67], v[232:235], v[216:219], v[64:67]
	v_mfma_f32_16x16x32_bf16 v[92:95], v[228:231], v[196:199], v[92:95]
	v_mfma_f32_16x16x32_bf16 v[88:91], v[236:239], v[196:199], v[88:91]
	v_mfma_f32_16x16x32_bf16 v[84:87], v[228:231], v[204:207], v[84:87]
	v_mfma_f32_16x16x32_bf16 v[80:83], v[236:239], v[204:207], v[80:83]
	v_mfma_f32_16x16x32_bf16 v[76:79], v[228:231], v[212:215], v[76:79]
	v_mfma_f32_16x16x32_bf16 v[72:75], v[236:239], v[212:215], v[72:75]
	v_mfma_f32_16x16x32_bf16 v[68:71], v[228:231], v[220:223], v[68:71]
	v_mfma_f32_16x16x32_bf16 v[64:67], v[236:239], v[220:223], v[64:67]
	s_setprio 0
	s_barrier
	ds_read_b128 v[192:195], v162 offset:16384
	ds_read_b128 v[196:199], v162 offset:17408
	ds_read_b128 v[200:203], v162 offset:18432
	ds_read_b128 v[204:207], v162 offset:19456
	s_add_u32 m0, s35, 0x0
	ds_read_b128 v[208:211], v162 offset:20480
	ds_read_b128 v[212:215], v162 offset:21504
	ds_read_b128 v[216:219], v162 offset:22528
	ds_read_b128 v[220:223], v162 offset:23552
	global_load_lds_dwordx4 v128, s[72:73]
	s_add_u32 m0, s35, 0x2000
	s_nop 0
	global_load_lds_dwordx4 v130, s[72:73]
	s_add_u32 s72, s72, 0x80
	s_addc_u32 s73, s73, 0
	s_barrier
	s_waitcnt lgkmcnt(0)
	s_setprio 1
	v_mfma_f32_16x16x32_bf16 v[60:63], v[176:179], v[192:195], v[60:63]
	v_mfma_f32_16x16x32_bf16 v[56:59], v[184:187], v[192:195], v[56:59]
	v_mfma_f32_16x16x32_bf16 v[52:55], v[176:179], v[200:203], v[52:55]
	v_mfma_f32_16x16x32_bf16 v[48:51], v[184:187], v[200:203], v[48:51]
	v_mfma_f32_16x16x32_bf16 v[44:47], v[176:179], v[208:211], v[44:47]
	v_mfma_f32_16x16x32_bf16 v[40:43], v[184:187], v[208:211], v[40:43]
	v_mfma_f32_16x16x32_bf16 v[36:39], v[176:179], v[216:219], v[36:39]
	v_mfma_f32_16x16x32_bf16 v[32:35], v[184:187], v[216:219], v[32:35]
	v_mfma_f32_16x16x32_bf16 v[60:63], v[180:183], v[196:199], v[60:63]
	v_mfma_f32_16x16x32_bf16 v[56:59], v[188:191], v[196:199], v[56:59]
	v_mfma_f32_16x16x32_bf16 v[52:55], v[180:183], v[204:207], v[52:55]
	v_mfma_f32_16x16x32_bf16 v[48:51], v[188:191], v[204:207], v[48:51]
	v_mfma_f32_16x16x32_bf16 v[44:47], v[180:183], v[212:215], v[44:47]
	v_mfma_f32_16x16x32_bf16 v[40:43], v[188:191], v[212:215], v[40:43]
	v_mfma_f32_16x16x32_bf16 v[36:39], v[180:183], v[220:223], v[36:39]
	v_mfma_f32_16x16x32_bf16 v[32:35], v[188:191], v[220:223], v[32:35]
	s_setprio 0
	s_barrier
	s_add_u32 m0, s35, 0x14000
	s_nop 0
	global_load_lds_dwordx4 v128, s[78:79]
	s_add_u32 m0, s35, 0x16000
	s_nop 0
	global_load_lds_dwordx4 v130, s[78:79]
	s_add_u32 s78, s78, 0x80
	s_addc_u32 s79, s79, 0
	s_waitcnt vmcnt(6)
	s_barrier
	s_setprio 1
	v_mfma_f32_16x16x32_bf16 v[28:31], v[224:227], v[192:195], v[28:31]
	v_mfma_f32_16x16x32_bf16 v[24:27], v[232:235], v[192:195], v[24:27]
	v_mfma_f32_16x16x32_bf16 v[20:23], v[224:227], v[200:203], v[20:23]
	v_mfma_f32_16x16x32_bf16 v[16:19], v[232:235], v[200:203], v[16:19]
	v_mfma_f32_16x16x32_bf16 v[12:15], v[224:227], v[208:211], v[12:15]
	v_mfma_f32_16x16x32_bf16 v[8:11], v[232:235], v[208:211], v[8:11]
	v_mfma_f32_16x16x32_bf16 v[4:7], v[224:227], v[216:219], v[4:7]
	v_mfma_f32_16x16x32_bf16 v[0:3], v[232:235], v[216:219], v[0:3]
	v_mfma_f32_16x16x32_bf16 v[28:31], v[228:231], v[196:199], v[28:31]
	v_mfma_f32_16x16x32_bf16 v[24:27], v[236:239], v[196:199], v[24:27]
	v_mfma_f32_16x16x32_bf16 v[20:23], v[228:231], v[204:207], v[20:23]
	v_mfma_f32_16x16x32_bf16 v[16:19], v[236:239], v[204:207], v[16:19]
	v_mfma_f32_16x16x32_bf16 v[12:15], v[228:231], v[212:215], v[12:15]
	v_mfma_f32_16x16x32_bf16 v[8:11], v[236:239], v[212:215], v[8:11]
	v_mfma_f32_16x16x32_bf16 v[4:7], v[228:231], v[220:223], v[4:7]
	v_mfma_f32_16x16x32_bf16 v[0:3], v[236:239], v[220:223], v[0:3]
	s_setprio 0
	s_barrier
	ds_read_b128 v[176:179], v164 offset:32768
	ds_read_b128 v[180:183], v164 offset:33792
	ds_read_b128 v[184:187], v164 offset:34816
	ds_read_b128 v[188:191], v164 offset:35840
	s_add_u32 m0, s35, 0x4000
	ds_read_b128 v[192:195], v162 offset:32768
	ds_read_b128 v[196:199], v162 offset:33792
	ds_read_b128 v[200:203], v162 offset:34816
	ds_read_b128 v[204:207], v162 offset:35840
	ds_read_b128 v[208:211], v162 offset:36864
	ds_read_b128 v[212:215], v162 offset:37888
	ds_read_b128 v[216:219], v162 offset:38912
	ds_read_b128 v[220:223], v162 offset:39936
	global_load_lds_dwordx4 v128, s[76:77]
	s_add_u32 m0, s35, 0x6000
	s_nop 0
	global_load_lds_dwordx4 v130, s[76:77]
	s_add_u32 s76, s76, 0x80
	s_addc_u32 s77, s77, 0
	s_waitcnt lgkmcnt(8)
	s_barrier
	s_waitcnt lgkmcnt(0)
	s_setprio 1
	v_mfma_f32_16x16x32_bf16 v[124:127], v[176:179], v[192:195], v[124:127]
	v_mfma_f32_16x16x32_bf16 v[120:123], v[184:187], v[192:195], v[120:123]
	v_mfma_f32_16x16x32_bf16 v[116:119], v[176:179], v[200:203], v[116:119]
	v_mfma_f32_16x16x32_bf16 v[112:115], v[184:187], v[200:203], v[112:115]
	v_mfma_f32_16x16x32_bf16 v[108:111], v[176:179], v[208:211], v[108:111]
	v_mfma_f32_16x16x32_bf16 v[104:107], v[184:187], v[208:211], v[104:107]
	v_mfma_f32_16x16x32_bf16 v[100:103], v[176:179], v[216:219], v[100:103]
	v_mfma_f32_16x16x32_bf16 v[96:99], v[184:187], v[216:219], v[96:99]
	v_mfma_f32_16x16x32_bf16 v[124:127], v[180:183], v[196:199], v[124:127]
	v_mfma_f32_16x16x32_bf16 v[120:123], v[188:191], v[196:199], v[120:123]
	v_mfma_f32_16x16x32_bf16 v[116:119], v[180:183], v[204:207], v[116:119]
	v_mfma_f32_16x16x32_bf16 v[112:115], v[188:191], v[204:207], v[112:115]
	v_mfma_f32_16x16x32_bf16 v[108:111], v[180:183], v[212:215], v[108:111]
	v_mfma_f32_16x16x32_bf16 v[104:107], v[188:191], v[212:215], v[104:107]
	v_mfma_f32_16x16x32_bf16 v[100:103], v[180:183], v[220:223], v[100:103]
	v_mfma_f32_16x16x32_bf16 v[96:99], v[188:191], v[220:223], v[96:99]
	s_setprio 0
	s_barrier
	ds_read_b128 v[224:227], v164 offset:49152
	ds_read_b128 v[228:231], v164 offset:50176
	ds_read_b128 v[232:235], v164 offset:51200
	ds_read_b128 v[236:239], v164 offset:52224
	s_add_u32 m0, s35, 0x18000
	global_load_lds_dwordx4 v128, s[42:43]
	s_add_u32 m0, s35, 0x1a000
	s_nop 0
	global_load_lds_dwordx4 v130, s[42:43]
	s_add_u32 s42, s42, 0x80
	s_addc_u32 s43, s43, 0
	s_barrier
	s_waitcnt lgkmcnt(0)
	s_setprio 1
	v_mfma_f32_16x16x32_bf16 v[92:95], v[224:227], v[192:195], v[92:95]
	v_mfma_f32_16x16x32_bf16 v[88:91], v[232:235], v[192:195], v[88:91]
	v_mfma_f32_16x16x32_bf16 v[84:87], v[224:227], v[200:203], v[84:87]
	v_mfma_f32_16x16x32_bf16 v[80:83], v[232:235], v[200:203], v[80:83]
	v_mfma_f32_16x16x32_bf16 v[76:79], v[224:227], v[208:211], v[76:79]
	v_mfma_f32_16x16x32_bf16 v[72:75], v[232:235], v[208:211], v[72:75]
	v_mfma_f32_16x16x32_bf16 v[68:71], v[224:227], v[216:219], v[68:71]
	v_mfma_f32_16x16x32_bf16 v[64:67], v[232:235], v[216:219], v[64:67]
	v_mfma_f32_16x16x32_bf16 v[92:95], v[228:231], v[196:199], v[92:95]
	v_mfma_f32_16x16x32_bf16 v[88:91], v[236:239], v[196:199], v[88:91]
	v_mfma_f32_16x16x32_bf16 v[84:87], v[228:231], v[204:207], v[84:87]
	v_mfma_f32_16x16x32_bf16 v[80:83], v[236:239], v[204:207], v[80:83]
	v_mfma_f32_16x16x32_bf16 v[76:79], v[228:231], v[212:215], v[76:79]
	v_mfma_f32_16x16x32_bf16 v[72:75], v[236:239], v[212:215], v[72:75]
	v_mfma_f32_16x16x32_bf16 v[68:71], v[228:231], v[220:223], v[68:71]
	v_mfma_f32_16x16x32_bf16 v[64:67], v[236:239], v[220:223], v[64:67]
	s_setprio 0
	s_barrier
	ds_read_b128 v[192:195], v162 offset:49152
	ds_read_b128 v[196:199], v162 offset:50176
	ds_read_b128 v[200:203], v162 offset:51200
	ds_read_b128 v[204:207], v162 offset:52224
	s_add_u32 m0, s35, 0x8000
	ds_read_b128 v[208:211], v162 offset:53248
	ds_read_b128 v[212:215], v162 offset:54272
	ds_read_b128 v[216:219], v162 offset:55296
	ds_read_b128 v[220:223], v162 offset:56320
	global_load_lds_dwordx4 v128, s[72:73]
	s_add_u32 m0, s35, 0xa000
	s_nop 0
	global_load_lds_dwordx4 v130, s[72:73]
	s_add_u32 s72, s72, 0x80
	s_addc_u32 s73, s73, 0
	s_barrier
	s_waitcnt lgkmcnt(0)
	s_setprio 1
	v_mfma_f32_16x16x32_bf16 v[60:63], v[176:179], v[192:195], v[60:63]
	v_mfma_f32_16x16x32_bf16 v[56:59], v[184:187], v[192:195], v[56:59]
	v_mfma_f32_16x16x32_bf16 v[52:55], v[176:179], v[200:203], v[52:55]
	v_mfma_f32_16x16x32_bf16 v[48:51], v[184:187], v[200:203], v[48:51]
	v_mfma_f32_16x16x32_bf16 v[44:47], v[176:179], v[208:211], v[44:47]
	v_mfma_f32_16x16x32_bf16 v[40:43], v[184:187], v[208:211], v[40:43]
	v_mfma_f32_16x16x32_bf16 v[36:39], v[176:179], v[216:219], v[36:39]
	v_mfma_f32_16x16x32_bf16 v[32:35], v[184:187], v[216:219], v[32:35]
	v_mfma_f32_16x16x32_bf16 v[60:63], v[180:183], v[196:199], v[60:63]
	v_mfma_f32_16x16x32_bf16 v[56:59], v[188:191], v[196:199], v[56:59]
	v_mfma_f32_16x16x32_bf16 v[52:55], v[180:183], v[204:207], v[52:55]
	v_mfma_f32_16x16x32_bf16 v[48:51], v[188:191], v[204:207], v[48:51]
	v_mfma_f32_16x16x32_bf16 v[44:47], v[180:183], v[212:215], v[44:47]
	v_mfma_f32_16x16x32_bf16 v[40:43], v[188:191], v[212:215], v[40:43]
	v_mfma_f32_16x16x32_bf16 v[36:39], v[180:183], v[220:223], v[36:39]
	v_mfma_f32_16x16x32_bf16 v[32:35], v[188:191], v[220:223], v[32:35]
	s_setprio 0
	s_barrier
	s_add_u32 m0, s35, 0x1c000
	s_nop 0
	global_load_lds_dwordx4 v128, s[78:79]
	s_add_u32 m0, s35, 0x1e000
	s_nop 0
	global_load_lds_dwordx4 v130, s[78:79]
	s_add_u32 s78, s78, 0x80
	s_addc_u32 s79, s79, 0
	s_waitcnt vmcnt(6)
	s_barrier
	s_setprio 1
	v_mfma_f32_16x16x32_bf16 v[28:31], v[224:227], v[192:195], v[28:31]
	v_mfma_f32_16x16x32_bf16 v[24:27], v[232:235], v[192:195], v[24:27]
	v_mfma_f32_16x16x32_bf16 v[20:23], v[224:227], v[200:203], v[20:23]
	v_mfma_f32_16x16x32_bf16 v[16:19], v[232:235], v[200:203], v[16:19]
	v_mfma_f32_16x16x32_bf16 v[12:15], v[224:227], v[208:211], v[12:15]
	v_mfma_f32_16x16x32_bf16 v[8:11], v[232:235], v[208:211], v[8:11]
	v_mfma_f32_16x16x32_bf16 v[4:7], v[224:227], v[216:219], v[4:7]
	v_mfma_f32_16x16x32_bf16 v[0:3], v[232:235], v[216:219], v[0:3]
	v_mfma_f32_16x16x32_bf16 v[28:31], v[228:231], v[196:199], v[28:31]
	v_mfma_f32_16x16x32_bf16 v[24:27], v[236:239], v[196:199], v[24:27]
	v_mfma_f32_16x16x32_bf16 v[20:23], v[228:231], v[204:207], v[20:23]
	v_mfma_f32_16x16x32_bf16 v[16:19], v[236:239], v[204:207], v[16:19]
	v_mfma_f32_16x16x32_bf16 v[12:15], v[228:231], v[212:215], v[12:15]
	v_mfma_f32_16x16x32_bf16 v[8:11], v[236:239], v[212:215], v[8:11]
	v_mfma_f32_16x16x32_bf16 v[4:7], v[228:231], v[220:223], v[4:7]
	v_mfma_f32_16x16x32_bf16 v[0:3], v[236:239], v[220:223], v[0:3]
	s_setprio 0
	s_cmp_lt_u32 s34, s3
	s_barrier
	s_cbranch_scc1 .LBB0_187
	s_mov_b64 s[72:73], 0x80
	s_mov_b64 s[76:77], 0x100
	s_mov_b64 s[78:79], 0x180
	s_add_i32 s66, s2, -1
	s_lshl_b64 s[2:3], s[66:67], 7
	s_add_u32 s2, s54, s2
	s_addc_u32 s3, s55, s3
	v_readfirstlane_b32 s34, v174
	v_lshl_add_u64 v[150:151], s[2:3], 0, v[128:129]
	s_mov_b32 m0, s34
	v_lshl_add_u64 v[130:131], s[2:3], 0, v[130:131]
	v_readfirstlane_b32 s2, v175
	ds_read_b128 v[132:135], v164
	ds_read_b128 v[136:139], v164 offset:1024
	ds_read_b128 v[140:143], v164 offset:2048
	ds_read_b128 v[144:147], v164 offset:3072
	ds_read_b128 v[158:161], v162
	ds_read_b128 v[166:169], v162 offset:1024
	ds_read_b128 v[170:173], v162 offset:2048
	ds_read_b128 v[176:179], v162 offset:3072
	ds_read_b128 v[180:183], v162 offset:4096
	ds_read_b128 v[184:187], v162 offset:5120
	ds_read_b128 v[188:191], v162 offset:6144
	ds_read_b128 v[192:195], v162 offset:7168
	global_load_lds_dwordx4 v[150:151], off
	s_mov_b32 m0, s2
	s_nop 0
	global_load_lds_dwordx4 v[130:131], off
	s_barrier
	s_waitcnt lgkmcnt(0)
	s_setprio 1
	s_waitcnt lgkmcnt(0)
	v_mfma_f32_16x16x32_bf16 v[124:127], v[132:135], v[158:161], v[124:127]
	v_mfma_f32_16x16x32_bf16 v[120:123], v[140:143], v[158:161], v[120:123]
	v_mfma_f32_16x16x32_bf16 v[116:119], v[132:135], v[170:173], v[116:119]
	v_mfma_f32_16x16x32_bf16 v[112:115], v[140:143], v[170:173], v[112:115]
	v_mfma_f32_16x16x32_bf16 v[100:103], v[132:135], v[188:191], v[100:103]
	v_mfma_f32_16x16x32_bf16 v[96:99], v[140:143], v[188:191], v[96:99]
	v_mfma_f32_16x16x32_bf16 v[124:127], v[136:139], v[166:169], v[124:127]
	v_mfma_f32_16x16x32_bf16 v[120:123], v[144:147], v[166:169], v[120:123]
	v_mfma_f32_16x16x32_bf16 v[116:119], v[136:139], v[176:179], v[116:119]
	v_mfma_f32_16x16x32_bf16 v[112:115], v[144:147], v[176:179], v[112:115]
	v_mfma_f32_16x16x32_bf16 v[108:111], v[132:135], v[180:183], v[108:111]
	v_mfma_f32_16x16x32_bf16 v[104:107], v[140:143], v[180:183], v[104:107]
	v_mfma_f32_16x16x32_bf16 v[100:103], v[136:139], v[192:195], v[100:103]
	v_mfma_f32_16x16x32_bf16 v[96:99], v[144:147], v[192:195], v[96:99]
	v_mfma_f32_16x16x32_bf16 v[196:199], v[136:139], v[184:187], v[108:111]
	v_mfma_f32_16x16x32_bf16 v[200:203], v[144:147], v[184:187], v[104:107]
	s_setprio 0
	s_barrier
	s_nop 1
	ds_read_b128 v[104:107], v164 offset:16384
	ds_read_b128 v[108:111], v164 offset:17408
	ds_read_b128 v[204:207], v164 offset:18432
	ds_read_b128 v[208:211], v164 offset:19456
	s_barrier
	s_waitcnt lgkmcnt(0)
	s_setprio 1
	s_waitcnt lgkmcnt(0)
	v_mfma_f32_16x16x32_bf16 v[84:87], v[104:107], v[170:173], v[84:87]
	v_mfma_f32_16x16x32_bf16 v[80:83], v[204:207], v[170:173], v[80:83]
	v_mfma_f32_16x16x32_bf16 v[68:71], v[104:107], v[188:191], v[68:71]
	v_mfma_f32_16x16x32_bf16 v[64:67], v[204:207], v[188:191], v[64:67]
	v_mfma_f32_16x16x32_bf16 v[92:95], v[104:107], v[158:161], v[92:95]
	v_mfma_f32_16x16x32_bf16 v[88:91], v[204:207], v[158:161], v[88:91]
	v_mfma_f32_16x16x32_bf16 v[84:87], v[108:111], v[176:179], v[84:87]
	v_mfma_f32_16x16x32_bf16 v[80:83], v[208:211], v[176:179], v[80:83]
	v_mfma_f32_16x16x32_bf16 v[76:79], v[104:107], v[180:183], v[76:79]
	v_mfma_f32_16x16x32_bf16 v[72:75], v[204:207], v[180:183], v[72:75]
	v_mfma_f32_16x16x32_bf16 v[68:71], v[108:111], v[192:195], v[68:71]
	v_mfma_f32_16x16x32_bf16 v[64:67], v[208:211], v[192:195], v[64:67]
	v_mfma_f32_16x16x32_bf16 v[212:215], v[108:111], v[166:169], v[92:95]
	v_mfma_f32_16x16x32_bf16 v[158:161], v[208:211], v[166:169], v[88:91]
	v_mfma_f32_16x16x32_bf16 v[166:169], v[108:111], v[184:187], v[76:79]
	v_mfma_f32_16x16x32_bf16 v[170:173], v[208:211], v[184:187], v[72:75]
	s_setprio 0
	s_barrier
	s_nop 0
	ds_read_b128 v[72:75], v162 offset:16384
	ds_read_b128 v[76:79], v162 offset:17408
	ds_read_b128 v[88:91], v162 offset:18432
	ds_read_b128 v[92:95], v162 offset:19456
	ds_read_b128 v[174:177], v162 offset:20480
	ds_read_b128 v[178:181], v162 offset:21504
	ds_read_b128 v[182:185], v162 offset:22528
	ds_read_b128 v[186:189], v162 offset:23552
	s_waitcnt vmcnt(4)
	s_barrier
	s_waitcnt lgkmcnt(0)
	s_setprio 1
	s_waitcnt lgkmcnt(0)
	v_mfma_f32_16x16x32_bf16 v[60:63], v[132:135], v[72:75], v[60:63]
	v_mfma_f32_16x16x32_bf16 v[56:59], v[140:143], v[72:75], v[56:59]
	v_mfma_f32_16x16x32_bf16 v[52:55], v[132:135], v[88:91], v[52:55]
	v_mfma_f32_16x16x32_bf16 v[48:51], v[140:143], v[88:91], v[48:51]
	v_mfma_f32_16x16x32_bf16 v[36:39], v[132:135], v[182:185], v[36:39]
	v_mfma_f32_16x16x32_bf16 v[32:35], v[140:143], v[182:185], v[32:35]
	v_mfma_f32_16x16x32_bf16 v[60:63], v[136:139], v[76:79], v[60:63]
	v_mfma_f32_16x16x32_bf16 v[56:59], v[144:147], v[76:79], v[56:59]
	v_mfma_f32_16x16x32_bf16 v[52:55], v[136:139], v[92:95], v[52:55]
	v_mfma_f32_16x16x32_bf16 v[48:51], v[144:147], v[92:95], v[48:51]
	v_mfma_f32_16x16x32_bf16 v[44:47], v[132:135], v[174:177], v[44:47]
	v_mfma_f32_16x16x32_bf16 v[40:43], v[140:143], v[174:177], v[40:43]
	v_mfma_f32_16x16x32_bf16 v[36:39], v[136:139], v[186:189], v[36:39]
	v_mfma_f32_16x16x32_bf16 v[32:35], v[144:147], v[186:189], v[32:35]
	v_mfma_f32_16x16x32_bf16 v[190:193], v[136:139], v[178:181], v[44:47]
	v_mfma_f32_16x16x32_bf16 v[216:219], v[144:147], v[178:181], v[40:43]
	s_setprio 0
	s_setprio 1
	v_mfma_f32_16x16x32_bf16 v[20:23], v[104:107], v[88:91], v[20:23]
	v_mfma_f32_16x16x32_bf16 v[16:19], v[204:207], v[88:91], v[16:19]
	v_mfma_f32_16x16x32_bf16 v[4:7], v[104:107], v[182:185], v[4:7]
	v_mfma_f32_16x16x32_bf16 v[0:3], v[204:207], v[182:185], v[0:3]
	v_mfma_f32_16x16x32_bf16 v[28:31], v[104:107], v[72:75], v[28:31]
	v_mfma_f32_16x16x32_bf16 v[24:27], v[204:207], v[72:75], v[24:27]
	v_mfma_f32_16x16x32_bf16 v[20:23], v[108:111], v[92:95], v[20:23]
	v_mfma_f32_16x16x32_bf16 v[16:19], v[208:211], v[92:95], v[16:19]
	v_mfma_f32_16x16x32_bf16 v[12:15], v[104:107], v[174:177], v[12:15]
	v_mfma_f32_16x16x32_bf16 v[8:11], v[204:207], v[174:177], v[8:11]
	v_mfma_f32_16x16x32_bf16 v[4:7], v[108:111], v[186:189], v[4:7]
	v_mfma_f32_16x16x32_bf16 v[0:3], v[208:211], v[186:189], v[0:3]
	v_mfma_f32_16x16x32_bf16 v[130:133], v[108:111], v[76:79], v[28:31]
	v_mfma_f32_16x16x32_bf16 v[134:137], v[208:211], v[76:79], v[24:27]
	v_mfma_f32_16x16x32_bf16 v[138:141], v[108:111], v[178:181], v[12:15]
	v_mfma_f32_16x16x32_bf16 v[142:145], v[208:211], v[178:181], v[8:11]
	s_setprio 0
	s_barrier
	s_nop 0
	ds_read_b128 v[8:11], v164 offset:32768
	ds_read_b128 v[12:15], v164 offset:33792
	ds_read_b128 v[174:177], v164 offset:34816
	ds_read_b128 v[178:181], v164 offset:35840
	ds_read_b128 v[24:27], v162 offset:32768
	ds_read_b128 v[28:31], v162 offset:33792
	ds_read_b128 v[40:43], v162 offset:34816
	ds_read_b128 v[44:47], v162 offset:35840
	ds_read_b128 v[182:185], v162 offset:36864
	ds_read_b128 v[186:189], v162 offset:37888
	ds_read_b128 v[204:207], v162 offset:38912
	ds_read_b128 v[208:211], v162 offset:39936
	s_waitcnt vmcnt(2)
	s_barrier
	s_waitcnt lgkmcnt(0)
	s_setprio 1
	s_waitcnt lgkmcnt(0)
	v_mfma_f32_16x16x32_bf16 v[72:75], v[8:11], v[24:27], v[124:127]
	v_mfma_f32_16x16x32_bf16 v[124:127], v[12:15], v[28:31], v[72:75]
	v_mfma_f32_16x16x32_bf16 v[72:75], v[174:177], v[24:27], v[120:123]
	v_mfma_f32_16x16x32_bf16 v[120:123], v[178:181], v[28:31], v[72:75]
	v_mfma_f32_16x16x32_bf16 v[72:75], v[8:11], v[40:43], v[116:119]
	v_mfma_f32_16x16x32_bf16 v[108:111], v[12:15], v[44:47], v[72:75]
	v_mfma_f32_16x16x32_bf16 v[72:75], v[174:177], v[40:43], v[112:115]
	v_mfma_f32_16x16x32_bf16 v[104:107], v[178:181], v[44:47], v[72:75]
	v_mfma_f32_16x16x32_bf16 v[72:75], v[8:11], v[182:185], v[196:199]
	v_mfma_f32_16x16x32_bf16 v[92:95], v[12:15], v[186:189], v[72:75]
	v_mfma_f32_16x16x32_bf16 v[72:75], v[174:177], v[182:185], v[200:203]
	v_mfma_f32_16x16x32_bf16 v[88:91], v[178:181], v[186:189], v[72:75]
	v_mfma_f32_16x16x32_bf16 v[72:75], v[8:11], v[204:207], v[100:103]
	v_mfma_f32_16x16x32_bf16 v[76:79], v[12:15], v[208:211], v[72:75]
	v_mfma_f32_16x16x32_bf16 v[72:75], v[174:177], v[204:207], v[96:99]
	v_mfma_f32_16x16x32_bf16 v[72:75], v[178:181], v[208:211], v[72:75]
	s_setprio 0
	s_barrier
	ds_read_b128 v[194:197], v164 offset:49152
	ds_read_b128 v[198:201], v164 offset:50176
	ds_read_b128 v[220:223], v164 offset:51200
	ds_read_b128 v[224:227], v164 offset:52224
	s_waitcnt vmcnt(0)
	s_barrier
	s_waitcnt lgkmcnt(0)
	s_setprio 1
	s_waitcnt lgkmcnt(0)
	v_mfma_f32_16x16x32_bf16 v[96:99], v[194:197], v[24:27], v[212:215]
	v_mfma_f32_16x16x32_bf16 v[24:27], v[220:223], v[24:27], v[158:161]
	v_mfma_f32_16x16x32_bf16 v[112:115], v[224:227], v[28:31], v[24:27]
	v_mfma_f32_16x16x32_bf16 v[24:27], v[194:197], v[40:43], v[84:87]
	v_mfma_f32_16x16x32_bf16 v[100:103], v[198:201], v[44:47], v[24:27]
	v_mfma_f32_16x16x32_bf16 v[24:27], v[220:223], v[40:43], v[80:83]
	v_mfma_f32_16x16x32_bf16 v[116:119], v[198:201], v[28:31], v[96:99]
	v_mfma_f32_16x16x32_bf16 v[96:99], v[224:227], v[44:47], v[24:27]
	v_mfma_f32_16x16x32_bf16 v[24:27], v[194:197], v[182:185], v[166:169]
	v_mfma_f32_16x16x32_bf16 v[84:87], v[198:201], v[186:189], v[24:27]
	v_mfma_f32_16x16x32_bf16 v[24:27], v[220:223], v[182:185], v[170:173]
	v_mfma_f32_16x16x32_bf16 v[80:83], v[224:227], v[186:189], v[24:27]
	v_mfma_f32_16x16x32_bf16 v[24:27], v[194:197], v[204:207], v[68:71]
	v_mfma_f32_16x16x32_bf16 v[68:71], v[198:201], v[208:211], v[24:27]
	v_mfma_f32_16x16x32_bf16 v[24:27], v[220:223], v[204:207], v[64:67]
	v_mfma_f32_16x16x32_bf16 v[64:67], v[224:227], v[208:211], v[24:27]
	s_setprio 0
	s_barrier
	ds_read_b128 v[158:161], v162 offset:49152
	ds_read_b128 v[164:167], v162 offset:50176
	ds_read_b128 v[168:171], v162 offset:51200
	ds_read_b128 v[182:185], v162 offset:52224
	ds_read_b128 v[186:189], v162 offset:53248
	ds_read_b128 v[202:205], v162 offset:54272
	ds_read_b128 v[206:209], v162 offset:55296
	ds_read_b128 v[210:213], v162 offset:56320
	s_barrier
	s_waitcnt lgkmcnt(0)
	s_setprio 1
	s_waitcnt lgkmcnt(0)
	v_mfma_f32_16x16x32_bf16 v[24:27], v[8:11], v[158:161], v[60:63]
	v_mfma_f32_16x16x32_bf16 v[60:63], v[12:15], v[164:167], v[24:27]
	v_mfma_f32_16x16x32_bf16 v[24:27], v[174:177], v[158:161], v[56:59]
	v_mfma_f32_16x16x32_bf16 v[56:59], v[178:181], v[164:167], v[24:27]
	v_mfma_f32_16x16x32_bf16 v[24:27], v[8:11], v[168:171], v[52:55]
	v_mfma_f32_16x16x32_bf16 v[44:47], v[12:15], v[182:185], v[24:27]
	v_mfma_f32_16x16x32_bf16 v[24:27], v[174:177], v[168:171], v[48:51]
	v_mfma_f32_16x16x32_bf16 v[40:43], v[178:181], v[182:185], v[24:27]
	v_mfma_f32_16x16x32_bf16 v[24:27], v[8:11], v[186:189], v[190:193]
	v_mfma_f32_16x16x32_bf16 v[8:11], v[8:11], v[206:209], v[36:39]
	v_mfma_f32_16x16x32_bf16 v[28:31], v[12:15], v[202:205], v[24:27]
	v_mfma_f32_16x16x32_bf16 v[24:27], v[174:177], v[186:189], v[216:219]
	v_mfma_f32_16x16x32_bf16 v[12:15], v[12:15], v[210:213], v[8:11]
	v_mfma_f32_16x16x32_bf16 v[8:11], v[174:177], v[206:209], v[32:35]
	v_mfma_f32_16x16x32_bf16 v[24:27], v[178:181], v[202:205], v[24:27]
	v_mfma_f32_16x16x32_bf16 v[8:11], v[178:181], v[210:213], v[8:11]
	s_setprio 0
	s_setprio 1
	v_mfma_f32_16x16x32_bf16 v[32:35], v[194:197], v[158:161], v[130:133]
	v_mfma_f32_16x16x32_bf16 v[52:55], v[198:201], v[164:167], v[32:35]
	v_mfma_f32_16x16x32_bf16 v[32:35], v[220:223], v[158:161], v[134:137]
	v_mfma_f32_16x16x32_bf16 v[16:19], v[220:223], v[168:171], v[16:19]
	v_mfma_f32_16x16x32_bf16 v[48:51], v[224:227], v[164:167], v[32:35]
	v_mfma_f32_16x16x32_bf16 v[20:23], v[194:197], v[168:171], v[20:23]
	v_mfma_f32_16x16x32_bf16 v[32:35], v[224:227], v[182:185], v[16:19]
	v_mfma_f32_16x16x32_bf16 v[16:19], v[194:197], v[186:189], v[138:141]
	v_mfma_f32_16x16x32_bf16 v[36:39], v[198:201], v[182:185], v[20:23]
	v_mfma_f32_16x16x32_bf16 v[20:23], v[198:201], v[202:205], v[16:19]
	v_mfma_f32_16x16x32_bf16 v[16:19], v[220:223], v[186:189], v[142:145]
	v_mfma_f32_16x16x32_bf16 v[4:7], v[194:197], v[206:209], v[4:7]
	v_mfma_f32_16x16x32_bf16 v[0:3], v[220:223], v[206:209], v[0:3]
	v_mfma_f32_16x16x32_bf16 v[16:19], v[224:227], v[202:205], v[16:19]
	v_mfma_f32_16x16x32_bf16 v[4:7], v[198:201], v[210:213], v[4:7]
	v_mfma_f32_16x16x32_bf16 v[0:3], v[224:227], v[210:213], v[0:3]
	s_setprio 0
	s_movk_i32 s2, 0x100
	v_cmp_gt_u32_e32 vcc, s2, v157
	s_barrier
	s_and_saveexec_b64 s[2:3], vcc
	s_cbranch_execz .LBB0_190
	s_barrier
